# grid barrier: all workgroups poll the monotonic cross-XCD arrival counter; XCD leader does writeback plus a no-return add
# speedup vs baseline: 1.0711x; 1.0023x over previous
; __device__ __forceinline__ unsigned xb_ld(unsigned* p)              { return __hip_atomic_load(p, __ATOMIC_RELAXED, __HIP_MEMORY_SCOPE_AGENT); }
; __device__ __forceinline__ unsigned xb_add(unsigned* p, unsigned v) { return __hip_atomic_fetch_add(p, v, __ATOMIC_RELAXED, __HIP_MEMORY_SCOPE_AGENT); }
; #define XB_SPIN(cond, bar) do { unsigned _sp = 0; while (cond) { __builtin_amdgcn_s_sleep(1); \
;     if ((++_sp & 255u) == 0u) { if (xb_ld(&(bar)[XB_TMO])) break; if (_sp > XB_SPIN_CAP) { atomicAdd(&(bar)[XB_TMO], 1u); break; } } } } while (0)
; __device__ __forceinline__ void xcd_barrier(const XcdBarrier& b) {
;     ...
;         const unsigned old = xb_add(&bar[XB_XSUB(b.x)], 1u);
;         const unsigned gen = old / nloc;
;         if (old + 1u == (gen + 1u) * nloc) {
;             __builtin_amdgcn_fence(__ATOMIC_RELEASE, "agent");
;             asm volatile("s_waitcnt vmcnt(0)" ::: "memory");
;             const unsigned og = xb_add(&bar[XB_TOP], 1u);
;             const unsigned tg = og / nx;
;             if (og + 1u == (tg + 1u) * nx) xb_add(&bar[XB_TOPGEN], 1u);
;             else XB_SPIN(xb_ld(&bar[XB_TOPGEN]) == tg, bar);
;             __builtin_amdgcn_fence(__ATOMIC_ACQUIRE, "agent");
;             xb_add(&bar[XB_XGEN(b.x)], 1u);
;             asm volatile("s_waitcnt vmcnt(0)" ::: "memory");
;         } else {
;             XB_SPIN(xb_ld(&bar[XB_XGEN(b.x)]) == gen, bar);
;             __builtin_amdgcn_fence(__ATOMIC_ACQUIRE, "agent");
;             asm volatile("s_waitcnt vmcnt(0)" ::: "memory");
.Lcg_243:
	s_or_b64 exec, exec, s[16:17]
	v_cvt_f32_u32_e32 v4, v2
	s_waitcnt vmcnt(0)
	v_readfirstlane_b32 s0, v3
	v_sub_u32_e32 v3, 0, v2
	v_rcp_iflag_f32_e32 v4, v4
	v_add_u32_e32 v5, s0, v1
	v_mul_f32_e32 v4, 0x4f7ffffe, v4
	v_cvt_u32_f32_e32 v4, v4
	v_mul_lo_u32 v1, v3, v4
	v_mul_hi_u32 v1, v4, v1
	v_add_u32_e32 v1, v4, v1
	v_mul_hi_u32 v1, v5, v1
	v_mul_lo_u32 v3, v1, v2
	v_sub_u32_e32 v3, v5, v3
	v_add_u32_e32 v4, 1, v1
	v_cmp_ge_u32_e32 vcc, v3, v2
	s_nop 1
	v_cndmask_b32_e32 v1, v1, v4, vcc
	v_sub_u32_e32 v4, v3, v2
	v_cndmask_b32_e32 v3, v3, v4, vcc
	v_add_u32_e32 v4, 1, v1
	v_cmp_ge_u32_e32 vcc, v3, v2
	v_add_u32_e32 v3, 1, v5
	s_nop 0
	v_cndmask_b32_e32 v1, v1, v4, vcc
	v_mul_lo_u32 v4, v2, v1
	v_add_u32_e32 v2, v4, v2
	v_cmp_ne_u32_e32 vcc, v3, v2
	s_cbranch_vccnz .Lxb_nl0
	buffer_wbl2 sc1
	s_waitcnt vmcnt(0) lgkmcnt(0)
	v_mov_b32_e32 v3, 0x83000
	v_mov_b32_e32 v4, 1
	global_atomic_add v3, v4, s[10:11] offset:1024
.Lxb_nl0:
	s_mov_b64 vcc, exec
	s_and_saveexec_b64 s[0:1], vcc
	s_xor_b64 s[14:15], exec, s[0:1]
	s_cbranch_execz .Lcg_257
	s_waitcnt lgkmcnt(0)
	v_mad_u32_u24 v1, v1, v0, v0
	v_mov_b32_e32 v0, 0x83000
	global_load_dword v0, v0, s[10:11] offset:1024 sc1
	s_add_u32 s20, s10, 0x83400
	s_addc_u32 s21, s11, 0
	s_waitcnt vmcnt(0)
	v_cmp_lt_u32_e32 vcc, v0, v1
	s_and_saveexec_b64 s[16:17], vcc
	s_cbranch_execz .Lcg_256
	s_add_u32 s18, s10, 0x80200
	s_addc_u32 s19, s11, 0
	s_mov_b32 s0, 1
	s_mov_b64 s[22:23], 0
	v_mov_b32_e32 v0, 0
	s_branch .Lcg_247

; __device__ __forceinline__ unsigned xb_ld(unsigned* p)              { return __hip_atomic_load(p, __ATOMIC_RELAXED, __HIP_MEMORY_SCOPE_AGENT); }
; #define XB_SPIN(cond, bar) do { unsigned _sp = 0; while (cond) { __builtin_amdgcn_s_sleep(1); \
;     if ((++_sp & 255u) == 0u) { if (xb_ld(&(bar)[XB_TMO])) break; if (_sp > XB_SPIN_CAP) { atomicAdd(&(bar)[XB_TMO], 1u); break; } } } } while (0)
; __device__ __forceinline__ void xcd_barrier(const XcdBarrier& b) {
;     ...
;             XB_SPIN(xb_ld(&bar[XB_XGEN(b.x)]) == gen, bar);
.Lcg_249:
	global_load_dword v2, v0, s[20:21] sc1
	s_add_i32 s0, s0, 1
	s_mov_b64 s[38:39], -1
	s_waitcnt vmcnt(0)
	v_cmp_ge_u32_e32 vcc, v2, v1
	s_orn2_b64 s[26:27], vcc, exec
	s_branch .Lcg_246

; __device__ __forceinline__ unsigned xb_ld(unsigned* p)              { return __hip_atomic_load(p, __ATOMIC_RELAXED, __HIP_MEMORY_SCOPE_AGENT); }
; __device__ __forceinline__ unsigned xb_add(unsigned* p, unsigned v) { return __hip_atomic_fetch_add(p, v, __ATOMIC_RELAXED, __HIP_MEMORY_SCOPE_AGENT); }
; #define XB_SPIN(cond, bar) do { unsigned _sp = 0; while (cond) { __builtin_amdgcn_s_sleep(1); \
;     if ((++_sp & 255u) == 0u) { if (xb_ld(&(bar)[XB_TMO])) break; if (_sp > XB_SPIN_CAP) { atomicAdd(&(bar)[XB_TMO], 1u); break; } } } } while (0)
; __device__ __forceinline__ void xcd_barrier(const XcdBarrier& b) {
;     ...
;         const unsigned old = xb_add(&bar[XB_XSUB(b.x)], 1u);
;         const unsigned gen = old / nloc;
;         if (old + 1u == (gen + 1u) * nloc) {
;             __builtin_amdgcn_fence(__ATOMIC_RELEASE, "agent");
;             asm volatile("s_waitcnt vmcnt(0)" ::: "memory");
;             const unsigned og = xb_add(&bar[XB_TOP], 1u);
;             const unsigned tg = og / nx;
;             if (og + 1u == (tg + 1u) * nx) xb_add(&bar[XB_TOPGEN], 1u);
;             else XB_SPIN(xb_ld(&bar[XB_TOPGEN]) == tg, bar);
;             __builtin_amdgcn_fence(__ATOMIC_ACQUIRE, "agent");
;             xb_add(&bar[XB_XGEN(b.x)], 1u);
;             asm volatile("s_waitcnt vmcnt(0)" ::: "memory");
;         } else {
;             XB_SPIN(xb_ld(&bar[XB_XGEN(b.x)]) == gen, bar);
;             __builtin_amdgcn_fence(__ATOMIC_ACQUIRE, "agent");
;             asm volatile("s_waitcnt vmcnt(0)" ::: "memory");
.LBB0_341:
	s_or_b64 exec, exec, s[18:19]
	v_cvt_f32_u32_e32 v4, v2
	s_waitcnt vmcnt(0)
	v_readfirstlane_b32 s0, v3
	v_sub_u32_e32 v3, 0, v2
	v_rcp_iflag_f32_e32 v4, v4
	v_add_u32_e32 v5, s0, v1
	v_mul_f32_e32 v4, 0x4f7ffffe, v4
	v_cvt_u32_f32_e32 v4, v4
	v_mul_lo_u32 v1, v3, v4
	v_mul_hi_u32 v1, v4, v1
	v_add_u32_e32 v1, v4, v1
	v_mul_hi_u32 v1, v5, v1
	v_mul_lo_u32 v3, v1, v2
	v_sub_u32_e32 v3, v5, v3
	v_add_u32_e32 v4, 1, v1
	v_cmp_ge_u32_e32 vcc, v3, v2
	s_nop 1
	v_cndmask_b32_e32 v1, v1, v4, vcc
	v_sub_u32_e32 v4, v3, v2
	v_cndmask_b32_e32 v3, v3, v4, vcc
	v_add_u32_e32 v4, 1, v1
	v_cmp_ge_u32_e32 vcc, v3, v2
	v_add_u32_e32 v3, 1, v5
	s_nop 0
	v_cndmask_b32_e32 v1, v1, v4, vcc
	v_mul_lo_u32 v4, v2, v1
	v_add_u32_e32 v2, v4, v2
	v_cmp_ne_u32_e32 vcc, v3, v2
	s_cbranch_vccnz .Lxb_nl2
	buffer_wbl2 sc1
	s_waitcnt vmcnt(0) lgkmcnt(0)
	v_mov_b32_e32 v3, 0x83000
	v_mov_b32_e32 v4, 1
	global_atomic_add v3, v4, s[12:13] offset:1024
.Lxb_nl2:
	s_mov_b64 vcc, exec
	s_and_saveexec_b64 s[0:1], vcc
	s_xor_b64 s[16:17], exec, s[0:1]
	s_cbranch_execz .LBB0_355
	s_waitcnt lgkmcnt(0)
	v_mad_u32_u24 v1, v1, v0, v0
	v_mov_b32_e32 v0, 0x83000
	global_load_dword v0, v0, s[12:13] offset:1024 sc1
	s_add_u32 s22, s12, 0x83400
	s_addc_u32 s23, s13, 0
	s_waitcnt vmcnt(0)
	v_cmp_lt_u32_e32 vcc, v0, v1
	s_and_saveexec_b64 s[18:19], vcc
	s_cbranch_execz .LBB0_354
	s_add_u32 s20, s12, 0x80200
	s_addc_u32 s21, s13, 0
	s_mov_b32 s0, 1
	s_mov_b64 s[24:25], 0
	v_mov_b32_e32 v0, 0
	s_branch .LBB0_345

; __device__ __forceinline__ unsigned xb_ld(unsigned* p)              { return __hip_atomic_load(p, __ATOMIC_RELAXED, __HIP_MEMORY_SCOPE_AGENT); }
; #define XB_SPIN(cond, bar) do { unsigned _sp = 0; while (cond) { __builtin_amdgcn_s_sleep(1); \
;     if ((++_sp & 255u) == 0u) { if (xb_ld(&(bar)[XB_TMO])) break; if (_sp > XB_SPIN_CAP) { atomicAdd(&(bar)[XB_TMO], 1u); break; } } } } while (0)
; __device__ __forceinline__ void xcd_barrier(const XcdBarrier& b) {
;     ...
;             XB_SPIN(xb_ld(&bar[XB_XGEN(b.x)]) == gen, bar);
.LBB0_347:
	global_load_dword v2, v0, s[22:23] sc1
	s_add_i32 s0, s0, 1
	s_mov_b64 s[40:41], -1
	s_waitcnt vmcnt(0)
	v_cmp_ge_u32_e32 vcc, v2, v1
	s_orn2_b64 s[38:39], vcc, exec
	s_branch .LBB0_344

; __device__ __forceinline__ unsigned xb_ld(unsigned* p)              { return __hip_atomic_load(p, __ATOMIC_RELAXED, __HIP_MEMORY_SCOPE_AGENT); }
; __device__ __forceinline__ unsigned xb_add(unsigned* p, unsigned v) { return __hip_atomic_fetch_add(p, v, __ATOMIC_RELAXED, __HIP_MEMORY_SCOPE_AGENT); }
; #define XB_SPIN(cond, bar) do { unsigned _sp = 0; while (cond) { __builtin_amdgcn_s_sleep(1); \
;     if ((++_sp & 255u) == 0u) { if (xb_ld(&(bar)[XB_TMO])) break; if (_sp > XB_SPIN_CAP) { atomicAdd(&(bar)[XB_TMO], 1u); break; } } } } while (0)
; __device__ __forceinline__ void xcd_barrier(const XcdBarrier& b) {
;     ...
;         const unsigned old = xb_add(&bar[XB_XSUB(b.x)], 1u);
;         const unsigned gen = old / nloc;
;         if (old + 1u == (gen + 1u) * nloc) {
;             __builtin_amdgcn_fence(__ATOMIC_RELEASE, "agent");
;             asm volatile("s_waitcnt vmcnt(0)" ::: "memory");
;             const unsigned og = xb_add(&bar[XB_TOP], 1u);
;             const unsigned tg = og / nx;
;             if (og + 1u == (tg + 1u) * nx) xb_add(&bar[XB_TOPGEN], 1u);
;             else XB_SPIN(xb_ld(&bar[XB_TOPGEN]) == tg, bar);
;             __builtin_amdgcn_fence(__ATOMIC_ACQUIRE, "agent");
;             xb_add(&bar[XB_XGEN(b.x)], 1u);
;             asm volatile("s_waitcnt vmcnt(0)" ::: "memory");
;         } else {
;             XB_SPIN(xb_ld(&bar[XB_XGEN(b.x)]) == gen, bar);
;             __builtin_amdgcn_fence(__ATOMIC_ACQUIRE, "agent");
;             asm volatile("s_waitcnt vmcnt(0)" ::: "memory");
.LBB0_675:
	s_or_b64 exec, exec, s[20:21]
	v_cvt_f32_u32_e32 v4, v2
	s_waitcnt vmcnt(0)
	v_readfirstlane_b32 s0, v3
	v_sub_u32_e32 v3, 0, v2
	v_rcp_iflag_f32_e32 v4, v4
	v_add_u32_e32 v5, s0, v1
	v_mul_f32_e32 v4, 0x4f7ffffe, v4
	v_cvt_u32_f32_e32 v4, v4
	v_mul_lo_u32 v1, v3, v4
	v_mul_hi_u32 v1, v4, v1
	v_add_u32_e32 v1, v4, v1
	v_mul_hi_u32 v1, v5, v1
	v_mul_lo_u32 v3, v1, v2
	v_sub_u32_e32 v3, v5, v3
	v_add_u32_e32 v4, 1, v1
	v_cmp_ge_u32_e32 vcc, v3, v2
	s_nop 1
	v_cndmask_b32_e32 v1, v1, v4, vcc
	v_sub_u32_e32 v4, v3, v2
	v_cndmask_b32_e32 v3, v3, v4, vcc
	v_add_u32_e32 v4, 1, v1
	v_cmp_ge_u32_e32 vcc, v3, v2
	v_add_u32_e32 v3, 1, v5
	s_nop 0
	v_cndmask_b32_e32 v1, v1, v4, vcc
	v_mul_lo_u32 v4, v2, v1
	v_add_u32_e32 v2, v4, v2
	v_cmp_ne_u32_e32 vcc, v3, v2
	s_cbranch_vccnz .Lxb_nl4
	buffer_wbl2 sc1
	s_waitcnt vmcnt(0) lgkmcnt(0)
	v_mov_b32_e32 v3, 0x83000
	v_mov_b32_e32 v4, 1
	global_atomic_add v3, v4, s[14:15] offset:1024
.Lxb_nl4:
	s_mov_b64 vcc, exec
	s_and_saveexec_b64 s[0:1], vcc
	s_xor_b64 s[18:19], exec, s[0:1]
	s_cbranch_execz .LBB0_689
	s_waitcnt lgkmcnt(0)
	v_mad_u32_u24 v1, v1, v0, v0
	v_mov_b32_e32 v0, 0x83000
	global_load_dword v0, v0, s[14:15] offset:1024 sc1
	s_add_u32 s24, s14, 0x83400
	s_addc_u32 s25, s15, 0
	s_waitcnt vmcnt(0)
	v_cmp_lt_u32_e32 vcc, v0, v1
	s_and_saveexec_b64 s[20:21], vcc
	s_cbranch_execz .LBB0_688
	s_add_u32 s22, s14, 0x80200
	s_addc_u32 s23, s15, 0
	s_mov_b32 s0, 1
	s_mov_b64 s[26:27], 0
	v_mov_b32_e32 v0, 0
	s_branch .LBB0_679

; __device__ __forceinline__ unsigned xb_ld(unsigned* p)              { return __hip_atomic_load(p, __ATOMIC_RELAXED, __HIP_MEMORY_SCOPE_AGENT); }
; #define XB_SPIN(cond, bar) do { unsigned _sp = 0; while (cond) { __builtin_amdgcn_s_sleep(1); \
;     if ((++_sp & 255u) == 0u) { if (xb_ld(&(bar)[XB_TMO])) break; if (_sp > XB_SPIN_CAP) { atomicAdd(&(bar)[XB_TMO], 1u); break; } } } } while (0)
; __device__ __forceinline__ void xcd_barrier(const XcdBarrier& b) {
;     ...
;             XB_SPIN(xb_ld(&bar[XB_XGEN(b.x)]) == gen, bar);
.LBB0_681:
	global_load_dword v2, v0, s[24:25] sc1
	s_add_i32 s0, s0, 1
	s_mov_b64 s[36:37], -1
	s_waitcnt vmcnt(0)
	v_cmp_ge_u32_e32 vcc, v2, v1
	s_orn2_b64 s[34:35], vcc, exec
	s_branch .LBB0_678

; __device__ __forceinline__ unsigned xb_ld(unsigned* p)              { return __hip_atomic_load(p, __ATOMIC_RELAXED, __HIP_MEMORY_SCOPE_AGENT); }
; __device__ __forceinline__ unsigned xb_add(unsigned* p, unsigned v) { return __hip_atomic_fetch_add(p, v, __ATOMIC_RELAXED, __HIP_MEMORY_SCOPE_AGENT); }
; #define XB_SPIN(cond, bar) do { unsigned _sp = 0; while (cond) { __builtin_amdgcn_s_sleep(1); \
;     if ((++_sp & 255u) == 0u) { if (xb_ld(&(bar)[XB_TMO])) break; if (_sp > XB_SPIN_CAP) { atomicAdd(&(bar)[XB_TMO], 1u); break; } } } } while (0)
; __device__ __forceinline__ void xcd_barrier(const XcdBarrier& b) {
;     ...
;         const unsigned old = xb_add(&bar[XB_XSUB(b.x)], 1u);
;         const unsigned gen = old / nloc;
;         if (old + 1u == (gen + 1u) * nloc) {
;             __builtin_amdgcn_fence(__ATOMIC_RELEASE, "agent");
;             asm volatile("s_waitcnt vmcnt(0)" ::: "memory");
;             const unsigned og = xb_add(&bar[XB_TOP], 1u);
;             const unsigned tg = og / nx;
;             if (og + 1u == (tg + 1u) * nx) xb_add(&bar[XB_TOPGEN], 1u);
;             else XB_SPIN(xb_ld(&bar[XB_TOPGEN]) == tg, bar);
;             __builtin_amdgcn_fence(__ATOMIC_ACQUIRE, "agent");
;             xb_add(&bar[XB_XGEN(b.x)], 1u);
;             asm volatile("s_waitcnt vmcnt(0)" ::: "memory");
;         } else {
;             XB_SPIN(xb_ld(&bar[XB_XGEN(b.x)]) == gen, bar);
;             __builtin_amdgcn_fence(__ATOMIC_ACQUIRE, "agent");
;             asm volatile("s_waitcnt vmcnt(0)" ::: "memory");
.LBB0_778:
	s_or_b64 exec, exec, s[20:21]
	v_cvt_f32_u32_e32 v4, v2
	s_waitcnt vmcnt(0)
	v_readfirstlane_b32 s0, v3
	v_sub_u32_e32 v3, 0, v2
	v_rcp_iflag_f32_e32 v4, v4
	v_add_u32_e32 v5, s0, v1
	v_mul_f32_e32 v4, 0x4f7ffffe, v4
	v_cvt_u32_f32_e32 v4, v4
	v_mul_lo_u32 v1, v3, v4
	v_mul_hi_u32 v1, v4, v1
	v_add_u32_e32 v1, v4, v1
	v_mul_hi_u32 v1, v5, v1
	v_mul_lo_u32 v3, v1, v2
	v_sub_u32_e32 v3, v5, v3
	v_add_u32_e32 v4, 1, v1
	v_cmp_ge_u32_e32 vcc, v3, v2
	s_nop 1
	v_cndmask_b32_e32 v1, v1, v4, vcc
	v_sub_u32_e32 v4, v3, v2
	v_cndmask_b32_e32 v3, v3, v4, vcc
	v_add_u32_e32 v4, 1, v1
	v_cmp_ge_u32_e32 vcc, v3, v2
	v_add_u32_e32 v3, 1, v5
	s_nop 0
	v_cndmask_b32_e32 v1, v1, v4, vcc
	v_mul_lo_u32 v4, v2, v1
	v_add_u32_e32 v2, v4, v2
	v_cmp_ne_u32_e32 vcc, v3, v2
	s_cbranch_vccnz .Lxb_nl5
	buffer_wbl2 sc1
	s_waitcnt vmcnt(0) lgkmcnt(0)
	v_mov_b32_e32 v3, 0x83000
	v_mov_b32_e32 v4, 1
	global_atomic_add v3, v4, s[12:13] offset:1024
.Lxb_nl5:
	s_mov_b64 vcc, exec
	s_and_saveexec_b64 s[0:1], vcc
	s_xor_b64 s[18:19], exec, s[0:1]
	s_cbranch_execz .LBB0_792
	s_waitcnt lgkmcnt(0)
	v_mad_u32_u24 v1, v1, v0, v0
	v_mov_b32_e32 v0, 0x83000
	global_load_dword v0, v0, s[12:13] offset:1024 sc1
	s_add_u32 s24, s12, 0x83400
	s_addc_u32 s25, s13, 0
	s_waitcnt vmcnt(0)
	v_cmp_lt_u32_e32 vcc, v0, v1
	s_and_saveexec_b64 s[20:21], vcc
	s_cbranch_execz .LBB0_791
	s_add_u32 s22, s12, 0x80200
	s_addc_u32 s23, s13, 0
	s_mov_b32 s0, 1
	s_mov_b64 s[26:27], 0
	v_mov_b32_e32 v0, 0
	s_branch .LBB0_782

; __device__ __forceinline__ unsigned xb_ld(unsigned* p)              { return __hip_atomic_load(p, __ATOMIC_RELAXED, __HIP_MEMORY_SCOPE_AGENT); }
; #define XB_SPIN(cond, bar) do { unsigned _sp = 0; while (cond) { __builtin_amdgcn_s_sleep(1); \
;     if ((++_sp & 255u) == 0u) { if (xb_ld(&(bar)[XB_TMO])) break; if (_sp > XB_SPIN_CAP) { atomicAdd(&(bar)[XB_TMO], 1u); break; } } } } while (0)
; __device__ __forceinline__ void xcd_barrier(const XcdBarrier& b) {
;     ...
;             XB_SPIN(xb_ld(&bar[XB_XGEN(b.x)]) == gen, bar);
.LBB0_784:
	global_load_dword v2, v0, s[24:25] sc1
	s_add_i32 s0, s0, 1
	s_mov_b64 s[34:35], -1
	s_waitcnt vmcnt(0)
	v_cmp_ge_u32_e32 vcc, v2, v1
	s_orn2_b64 s[30:31], vcc, exec
	s_branch .LBB0_781

; __device__ __forceinline__ unsigned xb_ld(unsigned* p)              { return __hip_atomic_load(p, __ATOMIC_RELAXED, __HIP_MEMORY_SCOPE_AGENT); }
; #define XB_SPIN(cond, bar) do { unsigned _sp = 0; while (cond) { __builtin_amdgcn_s_sleep(1); \
;     if ((++_sp & 255u) == 0u) { if (xb_ld(&(bar)[XB_TMO])) break; if (_sp > XB_SPIN_CAP) { atomicAdd(&(bar)[XB_TMO], 1u); break; } } } } while (0)
; __device__ __forceinline__ void xcd_barrier(const XcdBarrier& b) {
;     ...
;             XB_SPIN(xb_ld(&bar[XB_XGEN(b.x)]) == gen, bar);
.LBB0_1189:
	global_load_dword v2, v0, s[20:21] sc1
	s_add_i32 s0, s0, 1
	s_mov_b64 s[28:29], -1
	s_waitcnt vmcnt(0)
	v_cmp_ge_u32_e32 vcc, v2, v1
	s_orn2_b64 s[26:27], vcc, exec
	s_branch .LBB0_1186

; __device__ __forceinline__ unsigned xb_ld(unsigned* p)              { return __hip_atomic_load(p, __ATOMIC_RELAXED, __HIP_MEMORY_SCOPE_AGENT); }
; __device__ __forceinline__ unsigned xb_add(unsigned* p, unsigned v) { return __hip_atomic_fetch_add(p, v, __ATOMIC_RELAXED, __HIP_MEMORY_SCOPE_AGENT); }
; #define XB_SPIN(cond, bar) do { unsigned _sp = 0; while (cond) { __builtin_amdgcn_s_sleep(1); \
;     if ((++_sp & 255u) == 0u) { if (xb_ld(&(bar)[XB_TMO])) break; if (_sp > XB_SPIN_CAP) { atomicAdd(&(bar)[XB_TMO], 1u); break; } } } } while (0)
; __device__ __forceinline__ void xcd_barrier(const XcdBarrier& b) {
;     ...
;         const unsigned old = xb_add(&bar[XB_XSUB(b.x)], 1u);
;         const unsigned gen = old / nloc;
;         if (old + 1u == (gen + 1u) * nloc) {
;             __builtin_amdgcn_fence(__ATOMIC_RELEASE, "agent");
;             asm volatile("s_waitcnt vmcnt(0)" ::: "memory");
;             const unsigned og = xb_add(&bar[XB_TOP], 1u);
;             const unsigned tg = og / nx;
;             if (og + 1u == (tg + 1u) * nx) xb_add(&bar[XB_TOPGEN], 1u);
;             else XB_SPIN(xb_ld(&bar[XB_TOPGEN]) == tg, bar);
;             __builtin_amdgcn_fence(__ATOMIC_ACQUIRE, "agent");
;             xb_add(&bar[XB_XGEN(b.x)], 1u);
;             asm volatile("s_waitcnt vmcnt(0)" ::: "memory");
;         } else {
;             XB_SPIN(xb_ld(&bar[XB_XGEN(b.x)]) == gen, bar);
;             __builtin_amdgcn_fence(__ATOMIC_ACQUIRE, "agent");
;             asm volatile("s_waitcnt vmcnt(0)" ::: "memory");
.LBB0_1478:
	s_or_b64 exec, exec, s[14:15]
	v_cvt_f32_u32_e32 v4, v2
	s_waitcnt vmcnt(0)
	v_readfirstlane_b32 s0, v3
	v_sub_u32_e32 v3, 0, v2
	v_rcp_iflag_f32_e32 v4, v4
	v_add_u32_e32 v5, s0, v1
	v_mul_f32_e32 v4, 0x4f7ffffe, v4
	v_cvt_u32_f32_e32 v4, v4
	v_mul_lo_u32 v1, v3, v4
	v_mul_hi_u32 v1, v4, v1
	v_add_u32_e32 v1, v4, v1
	v_mul_hi_u32 v1, v5, v1
	v_mul_lo_u32 v3, v1, v2
	v_sub_u32_e32 v3, v5, v3
	v_add_u32_e32 v4, 1, v1
	v_cmp_ge_u32_e32 vcc, v3, v2
	s_nop 1
	v_cndmask_b32_e32 v1, v1, v4, vcc
	v_sub_u32_e32 v4, v3, v2
	v_cndmask_b32_e32 v3, v3, v4, vcc
	v_add_u32_e32 v4, 1, v1
	v_cmp_ge_u32_e32 vcc, v3, v2
	v_add_u32_e32 v3, 1, v5
	s_nop 0
	v_cndmask_b32_e32 v1, v1, v4, vcc
	v_mul_lo_u32 v4, v2, v1
	v_add_u32_e32 v2, v4, v2
	v_cmp_ne_u32_e32 vcc, v3, v2
	s_cbranch_vccnz .Lxb_nl7
	buffer_wbl2 sc1
	s_waitcnt vmcnt(0) lgkmcnt(0)
	v_mov_b32_e32 v3, 0x83000
	v_mov_b32_e32 v4, 1
	global_atomic_add v3, v4, s[8:9] offset:1024
.Lxb_nl7:
	s_mov_b64 vcc, exec
	s_and_saveexec_b64 s[0:1], vcc
	s_xor_b64 s[12:13], exec, s[0:1]
	s_cbranch_execz .LBB0_1492
	s_waitcnt lgkmcnt(0)
	v_mad_u32_u24 v1, v1, v0, v0
	v_mov_b32_e32 v0, 0x83000
	global_load_dword v0, v0, s[8:9] offset:1024 sc1
	s_add_u32 s18, s8, 0x83400
	s_addc_u32 s19, s9, 0
	s_waitcnt vmcnt(0)
	v_cmp_lt_u32_e32 vcc, v0, v1
	s_and_saveexec_b64 s[14:15], vcc
	s_cbranch_execz .LBB0_1491
	s_add_u32 s16, s8, 0x80200
	s_addc_u32 s17, s9, 0
	s_mov_b32 s0, 1
	s_mov_b64 s[20:21], 0
	v_mov_b32_e32 v0, 0
	s_branch .LBB0_1482

; __device__ __forceinline__ unsigned xb_ld(unsigned* p)              { return __hip_atomic_load(p, __ATOMIC_RELAXED, __HIP_MEMORY_SCOPE_AGENT); }
; #define XB_SPIN(cond, bar) do { unsigned _sp = 0; while (cond) { __builtin_amdgcn_s_sleep(1); \
;     if ((++_sp & 255u) == 0u) { if (xb_ld(&(bar)[XB_TMO])) break; if (_sp > XB_SPIN_CAP) { atomicAdd(&(bar)[XB_TMO], 1u); break; } } } } while (0)
; __device__ __forceinline__ void xcd_barrier(const XcdBarrier& b) {
;     ...
;             XB_SPIN(xb_ld(&bar[XB_XGEN(b.x)]) == gen, bar);
.LBB0_1484:
	global_load_dword v2, v0, s[18:19] sc1
	s_add_i32 s0, s0, 1
	s_mov_b64 s[26:27], -1
	s_waitcnt vmcnt(0)
	v_cmp_ge_u32_e32 vcc, v2, v1
	s_orn2_b64 s[24:25], vcc, exec
	s_branch .LBB0_1481
